# in-proj A K-loop LDS-DMA in SGPR-base+VGPR-offset form (no address VALU), 8 parked stores/wave trickled at 2 slots per K-iteration; INB 6 parked; wgmB=4; tblB
# speedup vs baseline: 1.0062x; 1.0062x over previous
; #define PG8_STAGE(bufoff, gbase, voff) do { _Pragma("unroll") for (int _i = 0; _i < 2; ++_i) \
;         __builtin_amdgcn_global_load_lds((const unsigned*)((const char*)(gbase) + (voff)[_i]), (PG8_LAS unsigned*)(lds + (bufoff) + ldsw + _i * 8192), 16, 0, 0); } while (0)
; #define PG8_LDA(dst, b, h) do { _Pragma("unroll") for (int m = 0; m < 4; ++m) _Pragma("unroll") for (int k = 0; k < 2; ++k) dst[m][k] = *(const PG8_LAS bf16x8*)(lds + PG8_SA(b, h) + aoff + m * 2048 + k * 1024); } while (0)
; #define PG8_LDB(dst, b, h) do { _Pragma("unroll") for (int n = 0; n < 2; ++n) _Pragma("unroll") for (int k = 0; k < 2; ++k) dst[n][k] = *(const PG8_LAS bf16x8*)(lds + PG8_SB(b, h) + boff + n * 2048 + k * 1024); } while (0)
; #define PG8_SCHED __builtin_amdgcn_sched_barrier(0)
;     ...
;         const bool has_next = S.next(ui + 1, nxt);
;         const char* nA = has_next ? (const char*)g.A + (size_t)nxt.pm * tstep : cA; const char* nB = has_next ? (const char*)g.Bt + (size_t)nxt.pn * tstep : cB;
;         for (int t = 0; t < nt; t += 2) {
;             const bool last = (t == nt - 2);
;             const char* a1 = cA + (size_t)(t + 1) * kstep;
;             const char* a2 = last ? nA : cA + (size_t)(t + 2) * kstep; const char* b2 = last ? nB : cB + (size_t)(t + 2) * kstep;
;             const char* a3 = a2 + kstep; const char* b3 = b2 + kstep;
;             PG8_LDB(B0, 0, 0); PG8_LDB(B1, 0, 1); PG8_SCHED; PG8_LDA(At, 0, 0); PG8_STAGE(PG8_SA(1, 1), a1 + hstep, voffA);
.LBB0_206:
	s_add_u32 s72, s38, 0xfffc0080
	s_addc_u32 s73, s39, -1
	s_add_i32 s82, 0, 0x10000
	s_cmp_eq_u32 s81, 12
	s_cselect_b32 s77, s2, s73
	s_cselect_b32 s76, s31, s72
	s_cselect_b32 s73, s29, s80
	s_cselect_b32 s72, s60, s61
	s_add_i32 s86, 0, 0x14000
	s_waitcnt lgkmcnt(0)
	v_add_u32_e32 v156, s82, v195
	v_add_u32_e32 v183, s86, v195
	ds_read_b128 v[144:147], v156
	ds_read_b128 v[148:151], v156 offset:1024
	ds_read_b128 v[152:155], v156 offset:2048
	ds_read_b128 v[156:159], v156 offset:3072
	ds_read_b128 v[186:189], v183
	ds_read_b128 v[198:201], v183 offset:1024
	ds_read_b128 v[202:205], v183 offset:2048
	ds_read_b128 v[206:209], v183 offset:3072
	s_add_i32 m0, s63, 0xc000
	ds_read_b128 v[210:213], v197
	ds_read_b128 v[214:217], v197 offset:1024
	ds_read_b128 v[218:221], v197 offset:2048
	ds_read_b128 v[222:225], v197 offset:3072
	ds_read_b128 v[226:229], v197 offset:4096
	ds_read_b128 v[230:233], v197 offset:5120
	ds_read_b128 v[234:237], v197 offset:6144
	ds_read_b128 v[238:241], v197 offset:7168
	global_load_lds_dwordx4 v178, s[38:39]
	s_add_i32 m0, s63, 0xe000
	s_nop 0
	global_load_lds_dwordx4 v180, s[38:39]
	s_lshl_b32 s100, s100, 1
	s_and_b32 s100, s100, 6
	s_cmp_eq_u32 s101, 0
	s_cbranch_scc1 .Lpka_na
	s_cmp_lt_i32 s81, 2
	s_cbranch_scc1 .Lpka_na
	s_or_b32 s100, s100, 1
	s_cmp_eq_u32 s101, 8
	s_cbranch_scc1 .Lpka_s0a
	s_cmp_eq_u32 s101, 7
	s_cbranch_scc1 .Lpka_s1a
	s_cmp_eq_u32 s101, 6
	s_cbranch_scc1 .Lpka_s2a
	s_cmp_eq_u32 s101, 5
	s_cbranch_scc1 .Lpka_s3a
	s_cmp_eq_u32 s101, 4
	s_cbranch_scc1 .Lpka_s4a
	s_cmp_eq_u32 s101, 3
	s_cbranch_scc1 .Lpka_s5a
	s_cmp_eq_u32 s101, 2
	s_cbranch_scc1 .Lpka_s6a
	global_store_dwordx4 v[254:255], v[12:15], off offset:64
	s_branch .Lpka_ia

; #define PG8_STAGE(bufoff, gbase, voff) do { _Pragma("unroll") for (int _i = 0; _i < 2; ++_i) \
;         __builtin_amdgcn_global_load_lds((const unsigned*)((const char*)(gbase) + (voff)[_i]), (PG8_LAS unsigned*)(lds + (bufoff) + ldsw + _i * 8192), 16, 0, 0); } while (0)
; #define PG8_LDA(dst, b, h) do { _Pragma("unroll") for (int m = 0; m < 4; ++m) _Pragma("unroll") for (int k = 0; k < 2; ++k) dst[m][k] = *(const PG8_LAS bf16x8*)(lds + PG8_SA(b, h) + aoff + m * 2048 + k * 1024); } while (0)
; #define PG8_WAIT_V(n) asm volatile("s_waitcnt vmcnt(" #n ")" ::: "memory")
; #define PG8_WAIT_L(n) asm volatile("s_waitcnt lgkmcnt(" #n ")" ::: "memory")
; #define PG8_BAR __builtin_amdgcn_s_barrier()
; #define PG8_SCHED __builtin_amdgcn_sched_barrier(0)
;     ...
;             PG8_WAIT_V(8); PG8_WAIT_L(0); PG8_BAR; PG8_MMA(0, 0, At, B0); PG8_MMA(0, 1, At, B1); PG8_BAR; PG8_SCHED;
;             PG8_LDA(At, 0, 1); PG8_STAGE(PG8_SB(0, 0), b2, voffB); PG8_STAGE(PG8_SB(0, 1), b2 + hstepB, voffB); PG8_STAGE(PG8_SA(0, 0), a2, voffA);
.Lpka_da:
	s_waitcnt lgkmcnt(0)
	s_barrier
	s_setprio 1
	s_waitcnt lgkmcnt(0)
	v_mfma_f32_16x16x32_bf16 v[132:135], v[144:147], v[210:213], v[132:135]
	v_mfma_f32_16x16x32_bf16 v[128:131], v[152:155], v[210:213], v[128:131]
	v_mfma_f32_16x16x32_bf16 v[116:119], v[144:147], v[218:221], v[116:119]
	v_mfma_f32_16x16x32_bf16 v[112:115], v[152:155], v[218:221], v[112:115]
	v_mfma_f32_16x16x32_bf16 v[100:103], v[144:147], v[226:229], v[100:103]
	v_mfma_f32_16x16x32_bf16 v[96:99], v[152:155], v[226:229], v[96:99]
	v_mfma_f32_16x16x32_bf16 v[84:87], v[144:147], v[234:237], v[84:87]
	v_mfma_f32_16x16x32_bf16 v[80:83], v[152:155], v[234:237], v[80:83]
	v_mfma_f32_16x16x32_bf16 v[132:135], v[148:151], v[214:217], v[132:135]
	v_mfma_f32_16x16x32_bf16 v[128:131], v[156:159], v[214:217], v[128:131]
	v_mfma_f32_16x16x32_bf16 v[116:119], v[148:151], v[222:225], v[116:119]
	v_mfma_f32_16x16x32_bf16 v[112:115], v[156:159], v[222:225], v[112:115]
	v_mfma_f32_16x16x32_bf16 v[100:103], v[148:151], v[230:233], v[100:103]
	v_mfma_f32_16x16x32_bf16 v[96:99], v[156:159], v[230:233], v[96:99]
	v_mfma_f32_16x16x32_bf16 v[84:87], v[148:151], v[238:241], v[84:87]
	v_mfma_f32_16x16x32_bf16 v[80:83], v[156:159], v[238:241], v[80:83]
	s_setprio 0
	s_setprio 1
	v_mfma_f32_16x16x32_bf16 v[140:143], v[186:189], v[210:213], v[140:143]
	v_mfma_f32_16x16x32_bf16 v[136:139], v[202:205], v[210:213], v[136:139]
	v_mfma_f32_16x16x32_bf16 v[124:127], v[186:189], v[218:221], v[124:127]
	v_mfma_f32_16x16x32_bf16 v[120:123], v[202:205], v[218:221], v[120:123]
	v_mfma_f32_16x16x32_bf16 v[108:111], v[186:189], v[226:229], v[108:111]
	v_mfma_f32_16x16x32_bf16 v[104:107], v[202:205], v[226:229], v[104:107]
	v_mfma_f32_16x16x32_bf16 v[92:95], v[186:189], v[234:237], v[92:95]
	v_mfma_f32_16x16x32_bf16 v[88:91], v[202:205], v[234:237], v[88:91]
	v_mfma_f32_16x16x32_bf16 v[140:143], v[198:201], v[214:217], v[140:143]
	v_mfma_f32_16x16x32_bf16 v[136:139], v[206:209], v[214:217], v[136:139]
	v_mfma_f32_16x16x32_bf16 v[124:127], v[198:201], v[222:225], v[124:127]
	v_mfma_f32_16x16x32_bf16 v[120:123], v[206:209], v[222:225], v[120:123]
	v_mfma_f32_16x16x32_bf16 v[108:111], v[198:201], v[230:233], v[108:111]
	v_mfma_f32_16x16x32_bf16 v[104:107], v[206:209], v[230:233], v[104:107]
	v_mfma_f32_16x16x32_bf16 v[92:95], v[198:201], v[238:241], v[92:95]
	v_mfma_f32_16x16x32_bf16 v[88:91], v[206:209], v[238:241], v[88:91]
	s_setprio 0
	s_barrier
	s_add_i32 s82, s82, s15
	s_mov_b32 m0, s82
	ds_read_b128 v[210:213], v197 offset:16384
	ds_read_b128 v[214:217], v197 offset:17408
	ds_read_b128 v[218:221], v197 offset:18432
	ds_read_b128 v[222:225], v197 offset:19456
	ds_read_b128 v[226:229], v197 offset:20480
	ds_read_b128 v[230:233], v197 offset:21504
	ds_read_b128 v[234:237], v197 offset:22528
	ds_read_b128 v[238:241], v197 offset:23552
	global_load_lds_dwordx4 v170, s[72:73]
	s_add_i32 m0, s82, 0x2000
	s_add_u32 s82, s72, 0x10000
	s_addc_u32 s83, s73, 0
	s_add_i32 s86, s86, s15
	global_load_lds_dwordx4 v166, s[72:73]
	s_mov_b32 m0, s86
	s_nop 0
	global_load_lds_dwordx4 v170, s[82:83]
	s_add_i32 m0, s86, 0x2000
	s_nop 0
	global_load_lds_dwordx4 v166, s[82:83]
	s_mov_b32 m0, s63
	s_nop 0
	global_load_lds_dwordx4 v172, s[76:77]
	s_mov_b32 m0, s64
	s_nop 0
	global_load_lds_dwordx4 v168, s[76:77]
	s_lshl_b32 s100, s100, 1
	s_and_b32 s100, s100, 6
	s_bcnt1_i32_b32 vcc_lo, s100
	s_cmp_eq_u32 vcc_lo, 0
	s_cbranch_scc1 .Lpka_w8b
	s_cmp_eq_u32 vcc_lo, 1
	s_cbranch_scc1 .Lpka_w9b
	s_waitcnt vmcnt(10)
	s_branch .Lpka_db

; #define PG8_STAGE(bufoff, gbase, voff) do { _Pragma("unroll") for (int _i = 0; _i < 2; ++_i) \
;         __builtin_amdgcn_global_load_lds((const unsigned*)((const char*)(gbase) + (voff)[_i]), (PG8_LAS unsigned*)(lds + (bufoff) + ldsw + _i * 8192), 16, 0, 0); } while (0)
; #define PG8_LDA(dst, b, h) do { _Pragma("unroll") for (int m = 0; m < 4; ++m) _Pragma("unroll") for (int k = 0; k < 2; ++k) dst[m][k] = *(const PG8_LAS bf16x8*)(lds + PG8_SA(b, h) + aoff + m * 2048 + k * 1024); } while (0)
; #define PG8_LDB(dst, b, h) do { _Pragma("unroll") for (int n = 0; n < 2; ++n) _Pragma("unroll") for (int k = 0; k < 2; ++k) dst[n][k] = *(const PG8_LAS bf16x8*)(lds + PG8_SB(b, h) + boff + n * 2048 + k * 1024); } while (0)
; #define PG8_WAIT_V(n) asm volatile("s_waitcnt vmcnt(" #n ")" ::: "memory")
; #define PG8_WAIT_L(n) asm volatile("s_waitcnt lgkmcnt(" #n ")" ::: "memory")
; #define PG8_BAR __builtin_amdgcn_s_barrier()
; #define PG8_SCHED __builtin_amdgcn_sched_barrier(0)
;     ...
;             PG8_WAIT_V(8); PG8_WAIT_L(0); PG8_BAR; PG8_MMA(1, 0, At, B0); PG8_MMA(1, 1, At, B1); PG8_BAR; PG8_SCHED;
;             PG8_LDB(B0, 1, 0); PG8_LDB(B1, 1, 1); PG8_SCHED; PG8_LDA(At, 1, 0); PG8_STAGE(PG8_SA(0, 1), a2 + hstep, voffA);
.Lpka_db:
	s_waitcnt lgkmcnt(0)
	s_barrier
	s_setprio 1
	s_waitcnt lgkmcnt(0)
	v_mfma_f32_16x16x32_bf16 v[68:71], v[144:147], v[210:213], v[68:71]
	v_mfma_f32_16x16x32_bf16 v[64:67], v[152:155], v[210:213], v[64:67]
	v_mfma_f32_16x16x32_bf16 v[52:55], v[144:147], v[218:221], v[52:55]
	v_mfma_f32_16x16x32_bf16 v[48:51], v[152:155], v[218:221], v[48:51]
	v_mfma_f32_16x16x32_bf16 v[36:39], v[144:147], v[226:229], v[36:39]
	v_mfma_f32_16x16x32_bf16 v[32:35], v[152:155], v[226:229], v[32:35]
	v_mfma_f32_16x16x32_bf16 v[20:23], v[144:147], v[234:237], v[20:23]
	v_mfma_f32_16x16x32_bf16 v[16:19], v[152:155], v[234:237], v[16:19]
	v_mfma_f32_16x16x32_bf16 v[68:71], v[148:151], v[214:217], v[68:71]
	v_mfma_f32_16x16x32_bf16 v[64:67], v[156:159], v[214:217], v[64:67]
	v_mfma_f32_16x16x32_bf16 v[52:55], v[148:151], v[222:225], v[52:55]
	v_mfma_f32_16x16x32_bf16 v[48:51], v[156:159], v[222:225], v[48:51]
	v_mfma_f32_16x16x32_bf16 v[36:39], v[148:151], v[230:233], v[36:39]
	v_mfma_f32_16x16x32_bf16 v[32:35], v[156:159], v[230:233], v[32:35]
	v_mfma_f32_16x16x32_bf16 v[20:23], v[148:151], v[238:241], v[20:23]
	v_mfma_f32_16x16x32_bf16 v[16:19], v[156:159], v[238:241], v[16:19]
	s_setprio 0
	s_setprio 1
	v_mfma_f32_16x16x32_bf16 v[76:79], v[186:189], v[210:213], v[76:79]
	v_mfma_f32_16x16x32_bf16 v[72:75], v[202:205], v[210:213], v[72:75]
	v_mfma_f32_16x16x32_bf16 v[60:63], v[186:189], v[218:221], v[60:63]
	v_mfma_f32_16x16x32_bf16 v[56:59], v[202:205], v[218:221], v[56:59]
	v_mfma_f32_16x16x32_bf16 v[44:47], v[186:189], v[226:229], v[44:47]
	v_mfma_f32_16x16x32_bf16 v[40:43], v[202:205], v[226:229], v[40:43]
	v_mfma_f32_16x16x32_bf16 v[24:27], v[186:189], v[234:237], v[24:27]
	v_mfma_f32_16x16x32_bf16 v[28:31], v[202:205], v[234:237], v[28:31]
	v_mfma_f32_16x16x32_bf16 v[76:79], v[198:201], v[214:217], v[76:79]
	v_mfma_f32_16x16x32_bf16 v[72:75], v[206:209], v[214:217], v[72:75]
	v_mfma_f32_16x16x32_bf16 v[60:63], v[198:201], v[222:225], v[60:63]
	v_mfma_f32_16x16x32_bf16 v[56:59], v[206:209], v[222:225], v[56:59]
	v_mfma_f32_16x16x32_bf16 v[44:47], v[198:201], v[230:233], v[44:47]
	v_mfma_f32_16x16x32_bf16 v[40:43], v[206:209], v[230:233], v[40:43]
	v_mfma_f32_16x16x32_bf16 v[24:27], v[198:201], v[238:241], v[24:27]
	v_mfma_f32_16x16x32_bf16 v[28:31], v[206:209], v[238:241], v[28:31]
	s_setprio 0
	s_barrier
	s_add_i32 s82, 0, 0x18000
	s_add_i32 s83, 0, 0x1c000
	v_add_u32_e32 v156, s82, v195
	v_add_u32_e32 v183, s83, v195
	ds_read_b128 v[144:147], v156
	ds_read_b128 v[148:151], v156 offset:1024
	ds_read_b128 v[152:155], v156 offset:2048
	ds_read_b128 v[156:159], v156 offset:3072
	ds_read_b128 v[186:189], v183
	ds_read_b128 v[198:201], v183 offset:1024
	ds_read_b128 v[202:205], v183 offset:2048
	ds_read_b128 v[206:209], v183 offset:3072
	s_add_u32 s76, s76, 0x40000
	s_addc_u32 s77, s77, 0
	s_mov_b32 m0, s65
	ds_read_b128 v[210:213], v197 offset:32768
	ds_read_b128 v[214:217], v197 offset:33792
	ds_read_b128 v[218:221], v197 offset:34816
	ds_read_b128 v[222:225], v197 offset:35840
	ds_read_b128 v[226:229], v197 offset:36864
	ds_read_b128 v[230:233], v197 offset:37888
	ds_read_b128 v[234:237], v197 offset:38912
	ds_read_b128 v[238:241], v197 offset:39936
	global_load_lds_dwordx4 v172, s[76:77]
	s_mov_b32 m0, s66
	s_nop 0
	global_load_lds_dwordx4 v168, s[76:77]
	s_lshl_b32 s100, s100, 1
	s_and_b32 s100, s100, 6
	s_cmp_eq_u32 s101, 0
	s_cbranch_scc1 .Lpka_nc
	s_cmp_lt_i32 s81, 2
	s_cbranch_scc1 .Lpka_nc
	s_or_b32 s100, s100, 1
	s_cmp_eq_u32 s101, 8
	s_cbranch_scc1 .Lpka_s0c
	s_cmp_eq_u32 s101, 7
	s_cbranch_scc1 .Lpka_s1c
	s_cmp_eq_u32 s101, 6
	s_cbranch_scc1 .Lpka_s2c
	s_cmp_eq_u32 s101, 5
	s_cbranch_scc1 .Lpka_s3c
	s_cmp_eq_u32 s101, 4
	s_cbranch_scc1 .Lpka_s4c
	s_cmp_eq_u32 s101, 3
	s_cbranch_scc1 .Lpka_s5c
	s_cmp_eq_u32 s101, 2
	s_cbranch_scc1 .Lpka_s6c
	global_store_dwordx4 v[254:255], v[12:15], off offset:64
	s_branch .Lpka_ic

; #define PG8_STAGE(bufoff, gbase, voff) do { _Pragma("unroll") for (int _i = 0; _i < 2; ++_i) \
;         __builtin_amdgcn_global_load_lds((const unsigned*)((const char*)(gbase) + (voff)[_i]), (PG8_LAS unsigned*)(lds + (bufoff) + ldsw + _i * 8192), 16, 0, 0); } while (0)
; #define PG8_LDA(dst, b, h) do { _Pragma("unroll") for (int m = 0; m < 4; ++m) _Pragma("unroll") for (int k = 0; k < 2; ++k) dst[m][k] = *(const PG8_LAS bf16x8*)(lds + PG8_SA(b, h) + aoff + m * 2048 + k * 1024); } while (0)
; #define PG8_WAIT_V(n) asm volatile("s_waitcnt vmcnt(" #n ")" ::: "memory")
; #define PG8_WAIT_L(n) asm volatile("s_waitcnt lgkmcnt(" #n ")" ::: "memory")
; #define PG8_BAR __builtin_amdgcn_s_barrier()
; #define PG8_SCHED __builtin_amdgcn_sched_barrier(0)
;     ...
;             PG8_WAIT_V(8); PG8_WAIT_L(0); PG8_BAR; PG8_MMA(0, 0, At, B0); PG8_MMA(0, 1, At, B1); PG8_BAR; PG8_SCHED;
;             PG8_LDA(At, 1, 1); PG8_STAGE(PG8_SB(1, 0), b3, voffB); PG8_STAGE(PG8_SB(1, 1), b3 + hstepB, voffB); PG8_STAGE(PG8_SA(1, 0), a3, voffA);
.Lpka_dc:
	s_waitcnt lgkmcnt(0)
	s_barrier
	s_setprio 1
	s_waitcnt lgkmcnt(0)
	v_mfma_f32_16x16x32_bf16 v[132:135], v[144:147], v[210:213], v[132:135]
	v_mfma_f32_16x16x32_bf16 v[128:131], v[152:155], v[210:213], v[128:131]
	v_mfma_f32_16x16x32_bf16 v[116:119], v[144:147], v[218:221], v[116:119]
	v_mfma_f32_16x16x32_bf16 v[112:115], v[152:155], v[218:221], v[112:115]
	v_mfma_f32_16x16x32_bf16 v[100:103], v[144:147], v[226:229], v[100:103]
	v_mfma_f32_16x16x32_bf16 v[96:99], v[152:155], v[226:229], v[96:99]
	v_mfma_f32_16x16x32_bf16 v[84:87], v[144:147], v[234:237], v[84:87]
	v_mfma_f32_16x16x32_bf16 v[80:83], v[152:155], v[234:237], v[80:83]
	v_mfma_f32_16x16x32_bf16 v[132:135], v[148:151], v[214:217], v[132:135]
	v_mfma_f32_16x16x32_bf16 v[128:131], v[156:159], v[214:217], v[128:131]
	v_mfma_f32_16x16x32_bf16 v[116:119], v[148:151], v[222:225], v[116:119]
	v_mfma_f32_16x16x32_bf16 v[112:115], v[156:159], v[222:225], v[112:115]
	v_mfma_f32_16x16x32_bf16 v[100:103], v[148:151], v[230:233], v[100:103]
	v_mfma_f32_16x16x32_bf16 v[96:99], v[156:159], v[230:233], v[96:99]
	v_mfma_f32_16x16x32_bf16 v[84:87], v[148:151], v[238:241], v[84:87]
	v_mfma_f32_16x16x32_bf16 v[80:83], v[156:159], v[238:241], v[80:83]
	s_setprio 0
	s_setprio 1
	v_mfma_f32_16x16x32_bf16 v[140:143], v[186:189], v[210:213], v[140:143]
	v_mfma_f32_16x16x32_bf16 v[136:139], v[202:205], v[210:213], v[136:139]
	v_mfma_f32_16x16x32_bf16 v[124:127], v[186:189], v[218:221], v[124:127]
	v_mfma_f32_16x16x32_bf16 v[120:123], v[202:205], v[218:221], v[120:123]
	v_mfma_f32_16x16x32_bf16 v[108:111], v[186:189], v[226:229], v[108:111]
	v_mfma_f32_16x16x32_bf16 v[104:107], v[202:205], v[226:229], v[104:107]
	v_mfma_f32_16x16x32_bf16 v[92:95], v[186:189], v[234:237], v[92:95]
	v_mfma_f32_16x16x32_bf16 v[88:91], v[202:205], v[234:237], v[88:91]
	v_mfma_f32_16x16x32_bf16 v[140:143], v[198:201], v[214:217], v[140:143]
	v_mfma_f32_16x16x32_bf16 v[136:139], v[206:209], v[214:217], v[136:139]
	v_mfma_f32_16x16x32_bf16 v[124:127], v[198:201], v[222:225], v[124:127]
	v_mfma_f32_16x16x32_bf16 v[120:123], v[206:209], v[222:225], v[120:123]
	v_mfma_f32_16x16x32_bf16 v[108:111], v[198:201], v[230:233], v[108:111]
	v_mfma_f32_16x16x32_bf16 v[104:107], v[206:209], v[230:233], v[104:107]
	v_mfma_f32_16x16x32_bf16 v[92:95], v[198:201], v[238:241], v[92:95]
	v_mfma_f32_16x16x32_bf16 v[88:91], v[206:209], v[238:241], v[88:91]
	s_setprio 0
	s_barrier
	s_add_i32 m0, s82, s15
	s_add_u32 vcc_lo, s72, 0x80
	s_addc_u32 vcc_hi, s73, 0
	ds_read_b128 v[210:213], v197 offset:49152
	ds_read_b128 v[214:217], v197 offset:50176
	ds_read_b128 v[218:221], v197 offset:51200
	ds_read_b128 v[222:225], v197 offset:52224
	ds_read_b128 v[226:229], v197 offset:53248
	ds_read_b128 v[230:233], v197 offset:54272
	ds_read_b128 v[234:237], v197 offset:55296
	ds_read_b128 v[238:241], v197 offset:56320
	global_load_lds_dwordx4 v170, vcc
	s_add_i32 m0, m0, 0x2000
	s_nop 0
	global_load_lds_dwordx4 v166, vcc
	s_add_u32 s72, s72, 0x10080
	s_addc_u32 s73, s73, 0
	s_add_i32 m0, s83, s15
	s_nop 0
	global_load_lds_dwordx4 v170, s[72:73]
	s_add_i32 m0, m0, 0x2000
	s_nop 0
	global_load_lds_dwordx4 v166, s[72:73]
	s_add_u32 vcc_lo, s76, 0xfffc0080
	s_addc_u32 vcc_hi, s77, -1
	s_mov_b32 m0, s74
	s_nop 0
	global_load_lds_dwordx4 v172, vcc
	s_mov_b32 m0, s75
	s_nop 0
	global_load_lds_dwordx4 v168, vcc
	s_lshl_b32 s100, s100, 1
	s_and_b32 s100, s100, 6
	s_bcnt1_i32_b32 vcc_lo, s100
	s_cmp_eq_u32 vcc_lo, 0
	s_cbranch_scc1 .Lpka_w8e
	s_cmp_eq_u32 vcc_lo, 1
	s_cbranch_scc1 .Lpka_w9e
	s_waitcnt vmcnt(10)
	s_branch .Lpka_de
